# LDS bank-conflict swizzle for the L6/L8 GEMM tiles: chunk index of rows 4..11 mod 16 XOR 1 in the ds_write base and both ds_read fragment bases (conflict-free ds_read_b128)
# baseline (speedup 1.0000x reference)
.LBB0_1134:
	s_or_b64 exec, exec, s[0:1]
	v_readlane_b32 s2, v247, 35
	v_readlane_b32 s3, v247, 36
	v_readlane_b32 s0, v249, 17
	s_waitcnt lgkmcnt(0)
	v_mov_b32_e32 v0, v172
	s_andn2_b64 vcc, exec, s[2:3]
	s_barrier
	s_cbranch_vccnz .LBB0_1139
	s_ashr_i32 s1, s0, 31
	s_lshl_b64 s[2:3], s[0:1], 21
	v_readlane_b32 s1, v250, 34
	s_add_u32 s4, s1, s2
	v_readlane_b32 s1, v250, 35
	s_addc_u32 s5, s1, s3
	v_ashrrev_i32_e32 v3, 7, v0
	v_lshlrev_b32_e32 v5, 4, v0
	s_movk_i32 s1, 0x60
	v_and_b32_e32 v2, 15, v0
	v_and_b32_e32 v6, 0x70, v5
	v_mov_b32_e32 v7, v149
	v_readlane_b32 s6, v247, 30
	v_mul_lo_u32 v166, v3, s1
	s_cmp_eq_u32 s0, 0
	v_ashrrev_i32_e32 v151, 3, v0
	v_bfe_u32 v1, v0, 4, 2
	v_and_b32_e32 v4, 64, v0
	v_readlane_b32 s7, v247, 31
	v_lshl_add_u64 v[154:155], s[4:5], 0, v[6:7]
	v_and_b32_e32 v5, 0x4f, v0
	v_or_b32_e32 v3, v166, v2
	s_cselect_b64 s[36:37], -1, 0
	s_mul_i32 s4, s0, 3
	v_and_b32_e32 v0, 7, v0
	s_add_u32 s0, s82, s2
	v_lshl_add_u64 v[152:153], s[6:7], 0, v[6:7]
	v_lshlrev_b32_e32 v7, 4, v1
	v_lshlrev_b32_e32 v167, 2, v1
	v_mul_lo_u32 v1, v151, s33
	v_mul_u32_u24_e32 v5, 0x90, v5
	v_mul_lo_u32 v3, v3, s33
	v_lshlrev_b32_e32 v148, 4, v0
	s_addc_u32 s1, s83, s3
	v_or_b32_e32 v168, 32, v167
	v_or_b32_e32 v169, 48, v167
	v_or_b32_e32 v170, 64, v167
	v_or_b32_e32 v171, 0x50, v167
	v_lshl_add_u64 v[156:157], s[82:83], 0, v[148:149]
	v_lshl_add_u64 v[158:159], s[0:1], 0, v[148:149]
	v_lshlrev_b32_e32 v148, 2, v4
	v_lshlrev_b32_e32 v160, 2, v2
	v_add_u32_e32 v204, v6, v1
	v_add_u32_e32 v205, v7, v5
	v_add_u32_e32 v206, v7, v3
	v_lshrrev_b32_e32 v220, 1, v151
	v_xor_b32_e32 v220, v220, v151
	v_bfe_u32 v220, v220, 2, 1
	v_and_b32_e32 v221, 1, v172
	v_lshlrev_b32_e32 v221, 5, v221
	v_sub_u32_e32 v221, 16, v221
	v_sub_u32_e32 v220, 0, v220
	v_and_b32_e32 v221, v221, v220
	v_add_u32_e32 v204, v204, v221
	v_and_b32_e32 v220, 15, v172
	v_lshrrev_b32_e32 v221, 1, v220
	v_xor_b32_e32 v220, v220, v221
	v_bfe_u32 v220, v220, 2, 1
	v_bfe_u32 v221, v172, 4, 1
	v_lshlrev_b32_e32 v221, 5, v221
	v_sub_u32_e32 v221, 16, v221
	v_sub_u32_e32 v220, 0, v220
	v_and_b32_e32 v221, v221, v220
	v_add_u32_e32 v205, v205, v221
	v_add_u32_e32 v206, v206, v221
	v_readlane_b32 s5, v247, 34
	v_readlane_b32 s7, v251, 3
	s_movk_i32 s24, 0x1800

.LBB0_1244:
	s_or_b64 exec, exec, s[0:1]
	v_readlane_b32 s2, v247, 35
	v_readlane_b32 s3, v247, 36
	s_mov_b32 s0, s44
	s_waitcnt lgkmcnt(0)
	v_mov_b32_e32 v0, v172
	s_and_b64 vcc, exec, s[2:3]
	s_barrier
	s_cbranch_vccz .LBB0_1274
	s_ashr_i32 s1, s0, 31
	s_lshl_b64 s[2:3], s[0:1], 15
	v_readlane_b32 s4, v250, 39
	v_readlane_b32 s5, v250, 40
	s_add_u32 s4, s4, s2
	s_addc_u32 s5, s5, s3
	s_lshl_b64 s[0:1], s[0:1], 21
	v_readlane_b32 s2, v250, 36
	s_add_u32 s2, s2, s0
	v_readlane_b32 s3, v250, 37
	s_addc_u32 s3, s3, s1
	s_getpc_b64 s[6:7]
	s_add_u32 s6, s6, STAIR@rel32@lo+4
	s_addc_u32 s7, s7, STAIR@rel32@hi+12
	v_and_b32_e32 v152, 15, v0
	s_getpc_b64 s[8:9]
	s_add_u32 s8, s8, STAIR@rel32@lo+20
	s_addc_u32 s9, s9, STAIR@rel32@hi+28
	global_load_ubyte v3, v152, s[6:7]
	global_load_ubyte v5, v152, s[8:9]
	s_getpc_b64 s[8:9]
	s_add_u32 s8, s8, STAIR@rel32@lo+36
	s_addc_u32 s9, s9, STAIR@rel32@hi+44
	v_and_or_b32 v1, v0, 63, 48
	global_load_ubyte v6, v152, s[8:9]
	global_load_ubyte v7, v1, s[6:7]
	s_movk_i32 s6, 0x7f
	v_bitop3_b32 v153, v0, s6, 15 bitop3:0x6c
	s_movk_i32 s6, 0x6f
	v_bitop3_b32 v155, v0, s6, 15 bitop3:0x6c
	s_movk_i32 s6, 0x5f
	v_ashrrev_i32_e32 v2, 6, v0
	v_bitop3_b32 v204, v0, s6, 15 bitop3:0x6c
	s_movk_i32 s6, 0x4f
	v_ashrrev_i32_e32 v151, 3, v0
	v_bfe_u32 v4, v0, 4, 2
	v_ashrrev_i32_e32 v8, 7, v0
	v_lshlrev_b32_e32 v9, 4, v0
	v_bitop3_b32 v205, v0, s6, 15 bitop3:0x6c
	v_and_b32_e32 v11, 1, v2
	s_movk_i32 s6, 0x60
	v_and_b32_e32 v154, 48, v0
	v_bitop3_b32 v206, v0, 63, 15 bitop3:0x6c
	v_bitop3_b32 v207, v0, 47, 15 bitop3:0x6c
	v_bitop3_b32 v208, v0, 31, 15 bitop3:0x6c
	v_bitop3_b32 v209, v0, 15, v0 bitop3:0xc
	v_and_b32_e32 v10, 7, v0
	v_and_b32_e32 v0, 0x70, v9
	v_mul_lo_u32 v8, v8, s6
	v_lshlrev_b32_e32 v210, 2, v4
	v_lshlrev_b32_e32 v211, 11, v2
	v_mul_lo_u32 v212, v2, 48
	v_lshlrev_b32_e32 v2, 3, v4
	v_lshlrev_b32_e32 v213, 8, v4
	v_lshlrev_b32_e32 v148, 7, v152
	v_mul_lo_u32 v4, v151, s33
	v_lshl_or_b32 v9, v11, 6, v152
	v_lshlrev_b32_e32 v11, 7, v11
	s_add_u32 s0, s82, s0
	v_or_b32_e32 v12, v8, v152
	v_or_b32_e32 v8, v210, v8
	v_add_u32_e32 v216, v0, v4
	v_lshl_or_b32 v4, v152, 1, v11
	v_lshl_add_u64 v[158:159], s[4:5], 0, v[148:149]
	s_movk_i32 s4, 0x110
	v_lshlrev_b32_e32 v148, 4, v10
	s_addc_u32 s1, s83, s1
	v_mov_b32_e32 v1, v149
	v_mul_u32_u24_e32 v9, 0x90, v9
	v_mul_lo_u32 v11, v12, s33
	v_lshl_add_u64 v[166:167], s[0:1], 0, v[148:149]
	s_movk_i32 s0, 0xff
	v_lshl_add_u64 v[156:157], s[90:91], 0, v[0:1]
	v_add_u32_e32 v214, 0xcc00, v211
	v_add_u32_e32 v215, 0xd000, v211
	v_add_u32_e32 v217, v154, v11
	v_lshl_add_u64 v[162:163], s[82:83], 0, v[148:149]
	v_lshl_add_u64 v[164:165], s[2:3], 0, v[0:1]
	v_lshlrev_b32_e32 v148, 1, v2
	s_waitcnt vmcnt(3)
	v_cmp_ne_u32_e64 s[36:37], s0, v3
	s_waitcnt vmcnt(2)
	v_mad_u64_u32 v[160:161], s[4:5], v8, s4, v[4:5]
	v_add_u32_e32 v161, v154, v9
	v_lshrrev_b32_e32 v9, 1, v151
	v_xor_b32_e32 v9, v9, v151
	v_bfe_u32 v9, v9, 2, 1
	v_and_b32_e32 v11, 1, v172
	v_lshlrev_b32_e32 v11, 5, v11
	v_sub_u32_e32 v11, 16, v11
	v_sub_u32_e32 v9, 0, v9
	v_and_b32_e32 v11, v11, v9
	v_add_u32_e32 v216, v216, v11
	v_and_b32_e32 v9, 15, v172
	v_lshrrev_b32_e32 v11, 1, v9
	v_xor_b32_e32 v9, v9, v11
	v_bfe_u32 v9, v9, 2, 1
	v_bfe_u32 v11, v172, 4, 1
	v_lshlrev_b32_e32 v11, 5, v11
	v_sub_u32_e32 v11, 16, v11
	v_sub_u32_e32 v9, 0, v9
	v_and_b32_e32 v11, v11, v9
	v_add_u32_e32 v217, v217, v11
	v_add_u32_e32 v161, v161, v11
	v_lshrrev_b32_e32 v218, 4, v3
	v_and_b32_e32 v219, 15, v3
	v_cmp_ne_u32_e64 s[38:39], s0, v5
	v_lshrrev_b32_e32 v220, 4, v5
	v_and_b32_e32 v221, 15, v5
	s_waitcnt vmcnt(1)
	v_cmp_ne_u32_e64 s[40:41], s0, v6
	v_lshrrev_b32_e32 v222, 4, v6
	v_and_b32_e32 v223, 15, v6
	s_waitcnt vmcnt(0)
	v_cmp_ne_u32_e64 s[42:43], s0, v7
	v_lshrrev_b32_e32 v224, 4, v7
	v_and_b32_e32 v225, 15, v7
	v_readlane_b32 s4, v247, 34
	s_branch .LBB0_1247
